# per-chunk decay (last token's cumulative product) stored to LDS straight from lane 15 of each row instead of rotating it to lane 0 with DPP
# speedup vs baseline: 1.0010x; 1.0010x over previous
.LBB0_328:
	v_mbcnt_lo_u32_b32 v248, -1, 0
	v_mbcnt_hi_u32_b32 v248, -1, v248
	s_waitcnt vmcnt(0)
	v_mov_b64_e32 v[152:153], v[138:139]
	v_and_b32_e32 v228, 63, v248
	v_lshl_add_u32 v194, v228, 4, 0
	v_mov_b64_e32 v[150:151], v[136:137]
	ds_read_b128 v[136:139], v194
	ds_read_b128 v[154:157], v194 offset:1024
	ds_read_b128 v[158:161], v194 offset:8192
	v_and_b32_e32 v246, 15, v248
	s_add_i32 s8, s7, s20
	v_add_u32_e32 v0, s8, v246
	s_waitcnt lgkmcnt(2)
	v_mfma_f32_16x16x32_bf16 v[136:139], v[136:139], v[144:147], 0
	v_sub_u32_e32 v1, s11, v246
	v_cndmask_b32_e64 v0, v1, v0, s[38:39]
	v_add_u32_e32 v0, s10, v0
	s_waitcnt lgkmcnt(1)
	v_mfma_f32_16x16x32_bf16 v[188:191], v[154:157], v[140:143], v[136:139]
	v_mov_b64_e32 v[170:171], s[4:5]
	v_bfe_u32 v249, v248, 4, 2
	v_mad_i64_i32 v[0:1], s[8:9], v0, s62, v[170:171]
	ds_read_b128 v[136:139], v194 offset:9216
	v_lshlrev_b64 v[172:173], 1, v[208:209]
	v_lshl_add_u64 v[0:1], v[0:1], 0, v[172:173]
	v_lshlrev_b32_e32 v2, 3, v249
	s_waitcnt lgkmcnt(1)
	v_mfma_f32_16x16x32_bf16 v[154:157], v[158:161], v[132:135], 0
	ds_read_b128 v[158:161], v194 offset:2048
	v_lshl_add_u64 v[0:1], v[0:1], 0, v[2:3]
	v_lshl_add_u64 v[162:163], v[0:1], 0, s[16:17]
	v_add_co_u32_e32 v0, vcc, s19, v0
	s_waitcnt lgkmcnt(1)
	v_mfma_f32_16x16x32_bf16 v[154:157], v[136:139], v[150:153], v[154:157]
	v_addc_co_u32_e32 v1, vcc, 0, v1, vcc
	ds_read_b128 v[136:139], v194 offset:3072
	v_mov_b64_e32 v[192:193], v[202:203]
	v_mov_b64_e32 v[232:233], v[240:241]
	v_mov_b64_e32 v[148:149], v[242:243]

	v_mov_b64_e32 v[0:1], v[244:245]
	ds_read_b128 v[162:165], v194 offset:10240
	ds_read_b128 v[166:169], v194 offset:11264
	s_waitcnt lgkmcnt(3)
	v_mfma_f32_16x16x32_bf16 v[158:161], v[158:161], v[144:147], 0
	s_mov_b32 s21, s20
	s_add_i32 s20, s20, 16
	s_cmpk_eq_i32 s21, 0xf0
	s_waitcnt lgkmcnt(2)
	v_mfma_f32_16x16x32_bf16 v[180:183], v[136:139], v[140:143], v[158:161]
	s_cselect_b32 s8, s21, s20
	s_add_i32 s8, s8, s7
	s_nop 0
	ds_read_b128 v[158:161], v194 offset:4096
	s_waitcnt lgkmcnt(2)
	v_mfma_f32_16x16x32_bf16 v[136:139], v[162:165], v[132:135], 0
	v_or_b32_e32 v174, s8, v246
	v_xad_u32 v175, v174, -1, s58
	v_cndmask_b32_e64 v162, v175, v174, s[38:39]
	s_waitcnt lgkmcnt(1)
	v_mfma_f32_16x16x32_bf16 v[176:179], v[166:169], v[150:153], v[136:139]
	v_add_u32_e32 v162, s10, v162
	v_mad_i64_i32 v[184:185], s[8:9], v162, s62, v[170:171]
	s_nop 0
	ds_read_b128 v[136:139], v194 offset:5120
	ds_read_b128 v[162:165], v194 offset:12288
	s_waitcnt lgkmcnt(2)
	v_mfma_f32_16x16x32_bf16 v[158:161], v[158:161], v[144:147], 0
	v_lshl_add_u64 v[166:167], v[184:185], 0, v[172:173]
	v_lshl_add_u64 v[170:171], v[166:167], 0, v[2:3]
	ds_read_b128 v[166:169], v194 offset:13312
	s_waitcnt lgkmcnt(2)
	v_mfma_f32_16x16x32_bf16 v[172:175], v[136:139], v[140:143], v[158:161]
	v_lshl_add_u64 v[186:187], v[170:171], 0, s[22:23]
	s_nop 1
	ds_read_b128 v[158:161], v194 offset:6144
	v_add_co_u32_e32 v170, vcc, s31, v170
	s_waitcnt lgkmcnt(2)
	v_mfma_f32_16x16x32_bf16 v[136:139], v[162:165], v[132:135], 0
	v_addc_co_u32_e32 v171, vcc, 0, v171, vcc
	v_mov_b64_e32 v[198:199], v[216:217]
	v_mov_b64_e32 v[196:197], v[214:215]
	v_mov_b64_e32 v[204:205], v[212:213]
	v_mov_b64_e32 v[206:207], v[210:211]
	global_load_dwordx2 v[210:211], v[170:171], off offset:2048
	global_load_dwordx2 v[212:213], v[186:187], off offset:32
	global_load_dwordx2 v[214:215], v[186:187], off offset:64
	global_load_dwordx2 v[216:217], v[186:187], off offset:96
	global_load_dwordx2 v[202:203], v[186:187], off offset:2048
	global_load_dwordx2 v[240:241], v[186:187], off offset:2080
	global_load_dwordx2 v[242:243], v[186:187], off offset:2112
	global_load_dwordx2 v[244:245], v[186:187], off offset:2144
	ds_read_b128 v[162:165], v194 offset:7168
	s_waitcnt lgkmcnt(2)
	v_mfma_f32_16x16x32_bf16 v[168:171], v[166:169], v[150:153], v[136:139]
	v_lshl_add_u64 v[166:167], v[184:185], 0, s[96:97]
	v_and_b32_e32 v200, 48, v248
	v_mov_b32_e32 v201, v3
	s_waitcnt lgkmcnt(1)
	v_mfma_f32_16x16x32_bf16 v[136:139], v[158:161], v[144:147], 0
	ds_read_b128 v[144:147], v194 offset:14336
	v_lshl_add_u64 v[158:159], v[166:167], 0, v[200:201]
	v_add_co_u32_e32 v220, vcc, s64, v158
	v_add_u32_e32 v250, 0, v200
	v_lshl_add_u64 v[218:219], v[158:159], 0, s[24:25]
	s_waitcnt lgkmcnt(1)
	v_mfma_f32_16x16x32_bf16 v[164:167], v[162:165], v[140:143], v[136:139]
	v_addc_co_u32_e32 v221, vcc, 0, v159, vcc
	ds_read_b128 v[158:161], v194 offset:15360
	s_waitcnt lgkmcnt(1)
	v_mfma_f32_16x16x32_bf16 v[184:187], v[144:147], v[132:135], 0
	ds_read_b128 v[132:135], v250 offset:17664
	ds_read_b128 v[136:139], v250 offset:17728
	v_lshlrev_b32_e32 v194, 16, v206
	v_and_b32_e32 v195, 0xffff0000, v206
	v_lshlrev_b32_e32 v234, 16, v207
	v_and_b32_e32 v235, 0xffff0000, v207
	v_lshlrev_b32_e32 v162, 16, v204
	v_and_b32_e32 v163, 0xffff0000, v204
	v_lshlrev_b32_e32 v236, 16, v205
	v_and_b32_e32 v237, 0xffff0000, v205
	s_waitcnt lgkmcnt(1)
	v_mul_f32_e32 v226, v134, v234
	v_mul_f32_e32 v227, v135, v235
	v_mul_f32_e32 v238, v132, v194
	v_mul_f32_e32 v239, v133, v195
	s_waitcnt lgkmcnt(0)
	v_mul_f32_e32 v132, v138, v236
	v_mul_f32_e32 v133, v139, v237
	v_mul_f32_e32 v134, v136, v162
	v_mul_f32_e32 v135, v137, v163
	v_mul_f32_e32 v132, v132, v132
	v_mul_f32_e32 v133, v133, v133
	v_mul_f32_e32 v134, v134, v134
	v_mul_f32_e32 v135, v135, v135
	v_fma_f32 v140, v226, v226, v132
	v_fma_f32 v141, v227, v227, v133
	v_fma_f32 v142, v238, v238, v134
	v_fma_f32 v143, v239, v239, v135
	ds_read_b128 v[132:135], v250 offset:17792
	ds_read_b128 v[136:139], v250 offset:17856
	v_lshlrev_b32_e32 v222, 16, v196
	v_and_b32_e32 v223, 0xffff0000, v196
	v_lshlrev_b32_e32 v224, 16, v197
	v_and_b32_e32 v225, 0xffff0000, v197
	s_waitcnt lgkmcnt(1)
	v_mul_f32_e32 v134, v134, v224
	v_mul_f32_e32 v135, v135, v225
	v_mul_f32_e32 v132, v132, v222
	v_mul_f32_e32 v133, v133, v223
	v_lshlrev_b32_e32 v196, 16, v198
	v_and_b32_e32 v197, 0xffff0000, v198
	v_lshlrev_b32_e32 v198, 16, v199
	v_and_b32_e32 v199, 0xffff0000, v199
	v_fma_f32 v134, v134, v134, v140
	v_fma_f32 v135, v135, v135, v141
	v_fma_f32 v132, v132, v132, v142
	v_fma_f32 v133, v133, v133, v143
	s_waitcnt lgkmcnt(0)
	v_mul_f32_e32 v138, v138, v198
	v_mul_f32_e32 v139, v139, v199
	v_mul_f32_e32 v136, v136, v196
	v_mul_f32_e32 v137, v137, v197
	v_fma_f32 v134, v138, v138, v134
	v_fma_f32 v135, v139, v139, v135
	v_fma_f32 v132, v136, v136, v132
	v_fma_f32 v133, v137, v137, v133
	v_lshlrev_b32_e32 v204, 2, v228
	v_pk_mov_b32 v[136:137], v[132:133], v[134:135] op_sel:[1,0]
	v_mov_b32_e32 v133, v135
	v_add_f32_e32 v132, v136, v132
	v_add_f32_e32 v133, v137, v133
	v_mfma_f32_16x16x32_bf16 v[150:153], v[158:161], v[150:153], v[184:187]
	v_add_f32_e32 v201, v132, v133
	v_xor_b32_e32 v132, 64, v204
	ds_bpermute_b32 v205, v132, v201
	global_load_dwordx4 v[132:135], v[218:219], off offset:256
	global_load_dwordx4 v[140:143], v[218:219], off offset:64
	global_load_dwordx4 v[144:147], v[220:221], off
	global_load_dwordx4 v[136:139], v[218:219], off offset:320
	ds_read_b128 v[218:221], v250 offset:17152
	v_xor_b32_e32 v158, 0x80, v204
	v_cmp_eq_u32_e64 s[40:41], 15, v246
	s_waitcnt lgkmcnt(1)
	v_add_f32_e32 v229, v201, v205

	s_waitcnt lgkmcnt(0)
	v_add_f32_e32 v188, v188, v218
	v_exp_f32_e32 v188, v188
	v_add_f32_e32 v189, v189, v219
	v_exp_f32_e32 v189, v189
	v_add_f32_e32 v190, v190, v220
	v_add_f32_e32 v188, 1.0, v188
	v_rcp_f32_e32 v188, v188
	v_add_f32_e32 v189, 1.0, v189
	v_rcp_f32_e32 v189, v189
	v_exp_f32_e32 v190, v190
	v_mul_f32_e32 v188, 0xbf60028a, v188
	v_exp_f32_e32 v188, v188
	v_add_f32_e32 v191, v191, v221
	v_add_f32_e32 v190, 1.0, v190
	v_rcp_f32_e32 v190, v190

	v_mul_f32_dpp v188, v188, v188 row_shr:1 row_mask:0xf bank_mask:0xf

	v_exp_f32_e32 v191, v191
	ds_bpermute_b32 v230, v158, v229

	v_mul_f32_dpp v188, v188, v188 row_shr:2 row_mask:0xf bank_mask:0xf

	v_add_f32_e32 v191, 1.0, v191
	v_rcp_f32_e32 v191, v191

	v_mul_f32_dpp v188, v188, v188 row_shr:4 row_mask:0xf bank_mask:0xf

	ds_read_b128 v[184:187], v250 offset:17408
	ds_read_b128 v[158:161], v250 offset:17920

	v_mul_f32_dpp v188, v188, v188 row_shr:8 row_mask:0xf bank_mask:0xf
	v_mov_b32_e32 v228, v188
	v_mul_f32_e32 v188, 0xbf60028a, v189
	v_exp_f32_e32 v189, v188

	v_mov_b32_e32 v218, 1.0
	v_mov_b32_e32 v219, 1.0

	v_mul_f32_dpp v189, v189, v189 row_shr:1 row_mask:0xf bank_mask:0xf

	v_mov_b32_e32 v220, 1.0
	v_mov_b32_e32 v221, 1.0

	v_mul_f32_dpp v189, v189, v189 row_shr:2 row_mask:0xf bank_mask:0xf

	v_mov_b32_dpp v218, v228 row_shr:1 row_mask:0xf bank_mask:0xf


	s_nop 0
	v_mul_f32_dpp v189, v189, v189 row_shr:4 row_mask:0xf bank_mask:0xf

	v_add_u32_e32 v247, s33, v200
	s_nop 0

	v_mul_f32_dpp v189, v189, v189 row_shr:8 row_mask:0xf bank_mask:0xf
	v_mov_b32_e32 v231, v189
	v_mul_f32_e32 v189, 0xbf60028a, v190
	v_exp_f32_e32 v190, v189

	v_mov_b32_dpp v219, v231 row_shr:1 row_mask:0xf bank_mask:0xf


	s_nop 0
	v_mul_f32_dpp v190, v190, v190 row_shr:1 row_mask:0xf bank_mask:0xf

	s_nop 1

	v_mul_f32_dpp v190, v190, v190 row_shr:2 row_mask:0xf bank_mask:0xf

	s_nop 1

	v_mul_f32_dpp v190, v190, v190 row_shr:4 row_mask:0xf bank_mask:0xf

	s_nop 1

	v_mul_f32_dpp v190, v190, v190 row_shr:8 row_mask:0xf bank_mask:0xf
	v_mov_b32_e32 v251, v190
	v_mul_f32_e32 v190, 0xbf60028a, v191
	v_exp_f32_e32 v191, v190

	v_mov_b32_dpp v220, v251 row_shr:1 row_mask:0xf bank_mask:0xf


	s_nop 0
	v_mul_f32_dpp v191, v191, v191 row_shr:1 row_mask:0xf bank_mask:0xf

	s_nop 1

	v_mul_f32_dpp v191, v191, v191 row_shr:2 row_mask:0xf bank_mask:0xf

	s_nop 1

	v_mul_f32_dpp v191, v191, v191 row_shr:4 row_mask:0xf bank_mask:0xf

	s_nop 1

	v_mul_f32_dpp v191, v191, v191 row_shr:8 row_mask:0xf bank_mask:0xf
	v_mov_b32_e32 v252, v191
	s_nop 1
	v_mov_b32_dpp v221, v252 row_shr:1 row_mask:0xf bank_mask:0xf

	s_and_saveexec_b64 s[8:9], s[40:41]
	ds_write_b32 v247, v228 offset:25856
	ds_write_b32 v247, v231 offset:25860
	ds_write_b32 v247, v251 offset:25864
	ds_write_b32 v247, v252 offset:25868
	s_or_b64 exec, exec, s[8:9]
	s_waitcnt lgkmcnt(2)
	v_add_f32_e32 v188, v229, v230
	v_mul_f32_e32 v189, 0x4f800000, v188
	v_cmp_gt_f32_e32 vcc, s69, v188
	s_waitcnt lgkmcnt(1)
	v_add_f32_e32 v154, v154, v184
	v_add_f32_e32 v155, v155, v185
	v_cndmask_b32_e32 v188, v188, v189, vcc
	v_sqrt_f32_e32 v189, v188
	v_add_f32_e32 v156, v156, v186
	v_add_f32_e32 v157, v157, v187
	v_exp_f32_e32 v154, v154
	v_add_u32_e32 v190, -1, v189
	v_fma_f32 v200, -v190, v189, v188
	v_add_u32_e32 v191, 1, v189
	v_cmp_ge_f32_e64 s[42:43], 0, v200
	v_exp_f32_e32 v155, v155
	v_exp_f32_e32 v156, v156
	v_cndmask_b32_e64 v190, v189, v190, s[42:43]
	v_fma_f32 v189, -v191, v189, v188
	v_cmp_lt_f32_e64 s[42:43], 0, v189
	v_exp_f32_e32 v157, v157
	v_add_f32_e32 v154, 1.0, v154
	v_cndmask_b32_e64 v189, v190, v191, s[42:43]
	v_mul_f32_e32 v190, 0x37800000, v189
	v_cndmask_b32_e32 v189, v189, v190, vcc
	v_cmp_class_f32_e64 vcc, v188, s100
	v_add_f32_e32 v155, 1.0, v155
	v_add_f32_e32 v156, 1.0, v156
	v_cndmask_b32_e32 v188, v189, v188, vcc
	v_max_f32_e32 v188, 0x2b8cbccc, v188
	v_div_scale_f32 v189, s[8:9], v188, v188, 1.0
	v_rcp_f32_e32 v190, v189
	v_add_f32_e32 v157, 1.0, v157
	v_rcp_f32_e32 v154, v154
	v_rcp_f32_e32 v155, v155
	v_fma_f32 v191, -v189, v190, 1.0
	v_fmac_f32_e32 v190, v191, v190
	v_div_scale_f32 v191, vcc, 1.0, v188, 1.0
	v_mul_f32_e32 v200, v191, v190
	v_fma_f32 v201, -v189, v200, v191
	v_rcp_f32_e32 v156, v156
	v_rcp_f32_e32 v157, v157
	v_fmac_f32_e32 v200, v201, v190
	v_fma_f32 v189, -v189, v200, v191
	v_div_fmas_f32 v189, v189, v190, v200
	v_rcp_f32_e32 v184, v228
	v_rcp_f32_e32 v185, v231
	v_rcp_f32_e32 v186, v251
	v_rcp_f32_e32 v187, v252
	v_div_fixup_f32 v230, v189, v188, 1.0
	v_add_f32_e32 v188, -1.0, v154
	v_add_f32_e32 v189, -1.0, v155
	v_add_f32_e32 v190, -1.0, v156
	v_add_f32_e32 v191, -1.0, v157
	v_mul_f32_e32 v228, v226, v230
	v_mul_f32_e32 v229, v227, v230
	s_waitcnt lgkmcnt(0)
	v_fma_f32 v160, v160, v190, 1.0
	v_fma_f32 v161, v161, v191, 1.0
	v_fma_f32 v158, v158, v188, 1.0
	v_fma_f32 v159, v159, v189, 1.0
	v_mul_f32_e32 v226, v238, v230
	v_mul_f32_e32 v227, v239, v230
	v_mul_f32_e32 v158, v158, v194
	v_mul_f32_e32 v159, v159, v195
	v_mul_f32_e32 v160, v160, v234
	v_mul_f32_e32 v161, v161, v235
	v_mul_f32_e32 v156, v156, v228
	v_mul_f32_e32 v157, v157, v229
	v_mad_u32_u24 v2, v246, s63, v2
	v_mul_f32_e32 v154, v154, v226
	v_mul_f32_e32 v155, v155, v227
	v_mul_f32_e32 v188, v156, v186
	v_mul_f32_e32 v189, v157, v187
	v_mul_f32_e32 v156, v160, v186
	v_mul_f32_e32 v157, v161, v187
	v_mul_f32_e32 v158, v158, v184
	v_mul_f32_e32 v159, v159, v185
	v_mul_f32_e32 v154, v154, v184
	v_mul_f32_e32 v155, v155, v185
	v_cvt_pk_bf16_f32 v160, v158, v159
	v_cvt_pk_bf16_f32 v161, v156, v157
	v_add_u32_e32 v2, s33, v2
	v_cvt_pk_bf16_f32 v156, v154, v155
	v_cvt_pk_bf16_f32 v157, v188, v189
	ds_write_b64 v2, v[160:161] offset:21248
	ds_write_b64 v2, v[156:157] offset:23552

	ds_write_b64 v2, v[192:193] offset:18944
	ds_read_b128 v[204:207], v250 offset:17216
	ds_read_b128 v[192:195], v250 offset:17472
	ds_read_b128 v[188:191], v250 offset:17728
	ds_read_b128 v[184:187], v250 offset:17984

	s_waitcnt lgkmcnt(3)
	v_add_f32_e32 v158, v182, v206
	v_exp_f32_e32 v158, v158
	v_add_f32_e32 v155, v181, v205
	v_add_f32_e32 v154, v180, v204
	v_add_f32_e32 v159, v183, v207
	v_add_f32_e32 v158, 1.0, v158
	v_rcp_f32_e32 v181, v158
	v_exp_f32_e32 v154, v154
	v_exp_f32_e32 v155, v155
	v_exp_f32_e32 v159, v159
	v_mul_f32_e32 v181, 0xbf60028a, v181
	v_exp_f32_e32 v183, v181
	v_add_f32_e32 v154, 1.0, v154
	v_add_f32_e32 v155, 1.0, v155
	v_add_f32_e32 v158, 1.0, v159

	v_mul_f32_dpp v183, v183, v183 row_shr:1 row_mask:0xf bank_mask:0xf

	v_rcp_f32_e32 v154, v154
	v_rcp_f32_e32 v155, v155
	v_rcp_f32_e32 v182, v158

	v_mul_f32_dpp v183, v183, v183 row_shr:2 row_mask:0xf bank_mask:0xf

	v_mul_f32_e32 v154, 0xbf60028a, v154
	v_mul_f32_e32 v155, 0xbf60028a, v155

	v_mul_f32_dpp v183, v183, v183 row_shr:4 row_mask:0xf bank_mask:0xf

	v_mul_f32_e32 v182, 0xbf60028a, v182
	v_exp_f32_e32 v154, v154

	v_exp_f32_e32 v155, v155
	v_mul_f32_dpp v183, v183, v183 row_shr:8 row_mask:0xf bank_mask:0xf
	v_mov_b32_e32 v238, v183
	v_exp_f32_e32 v183, v182


	v_mul_f32_dpp v154, v154, v154 row_shr:1 row_mask:0xf bank_mask:0xf

	v_mul_f32_dpp v155, v155, v155 row_shr:1 row_mask:0xf bank_mask:0xf

	v_mul_f32_dpp v183, v183, v183 row_shr:1 row_mask:0xf bank_mask:0xf


	v_mul_f32_dpp v154, v154, v154 row_shr:2 row_mask:0xf bank_mask:0xf

	v_mul_f32_dpp v155, v155, v155 row_shr:2 row_mask:0xf bank_mask:0xf

	v_mul_f32_dpp v183, v183, v183 row_shr:2 row_mask:0xf bank_mask:0xf


	v_mul_f32_dpp v154, v154, v154 row_shr:4 row_mask:0xf bank_mask:0xf

	v_mul_f32_dpp v155, v155, v155 row_shr:4 row_mask:0xf bank_mask:0xf

	v_mul_f32_dpp v183, v183, v183 row_shr:4 row_mask:0xf bank_mask:0xf


	v_mul_f32_dpp v154, v154, v154 row_shr:8 row_mask:0xf bank_mask:0xf
	v_mov_b32_e32 v158, v154
	v_mov_b32_e32 v154, 1.0
	v_mul_f32_dpp v155, v155, v155 row_shr:8 row_mask:0xf bank_mask:0xf
	v_mov_b32_e32 v159, v155
	v_mov_b32_e32 v155, 1.0
	v_mov_b32_e32 v234, 1.0
	v_mul_f32_dpp v183, v183, v183 row_shr:8 row_mask:0xf bank_mask:0xf
	v_mov_b32_e32 v239, v183
	v_mov_b32_e32 v235, 1.0
	v_mov_b32_dpp v154, v158 row_shr:1 row_mask:0xf bank_mask:0xf

	v_mov_b32_dpp v155, v159 row_shr:1 row_mask:0xf bank_mask:0xf

	v_mov_b32_dpp v234, v238 row_shr:1 row_mask:0xf bank_mask:0xf

	v_mov_b32_dpp v235, v239 row_shr:1 row_mask:0xf bank_mask:0xf

	s_and_saveexec_b64 s[8:9], s[40:41]
	ds_write_b64 v247, v[158:159] offset:25920
	ds_write_b64 v247, v[238:239] offset:25928
	s_or_b64 exec, exec, s[8:9]
	s_waitcnt lgkmcnt(2)
	v_add_f32_e32 v176, v176, v192
	v_add_f32_e32 v177, v177, v193
	v_add_f32_e32 v178, v178, v194
	v_add_f32_e32 v179, v179, v195
	v_exp_f32_e32 v176, v176
	v_exp_f32_e32 v177, v177
	v_exp_f32_e32 v178, v178
	v_exp_f32_e32 v179, v179
	v_add_f32_e32 v176, 1.0, v176
	v_add_f32_e32 v177, 1.0, v177
	v_add_f32_e32 v178, 1.0, v178
	v_add_f32_e32 v179, 1.0, v179
	v_rcp_f32_e32 v176, v176
	v_rcp_f32_e32 v177, v177
	v_rcp_f32_e32 v178, v178
	v_rcp_f32_e32 v179, v179
	v_rcp_f32_e32 v158, v158
	v_rcp_f32_e32 v159, v159
	v_rcp_f32_e32 v180, v238
	v_rcp_f32_e32 v181, v239
	s_waitcnt lgkmcnt(1)
	v_mul_f32_e32 v182, v190, v236
	v_mul_f32_e32 v183, v191, v237
	v_mov_b32_e32 v238, v230
	v_mov_b32_e32 v239, v230
	v_mov_b32_e32 v231, v230
	v_mul_f32_e32 v188, v188, v162
	v_mul_f32_e32 v189, v189, v163
	v_mul_f32_e32 v190, v238, v182
	v_mul_f32_e32 v191, v239, v183
	v_add_f32_e32 v182, -1.0, v176
	v_add_f32_e32 v183, -1.0, v177
	v_add_f32_e32 v192, -1.0, v178
	v_add_f32_e32 v193, -1.0, v179
	v_mul_f32_e32 v188, v230, v188
	v_mul_f32_e32 v189, v231, v189
	s_waitcnt lgkmcnt(0)
	v_fma_f32 v186, v186, v192, 1.0
	v_fma_f32 v187, v187, v193, 1.0
	v_fma_f32 v182, v184, v182, 1.0
	v_fma_f32 v183, v185, v183, 1.0
	v_mul_f32_e32 v178, v190, v178
	v_mul_f32_e32 v179, v191, v179
	v_mul_f32_e32 v162, v182, v162
	v_mul_f32_e32 v163, v183, v163
	v_mul_f32_e32 v182, v186, v236
	v_mul_f32_e32 v183, v187, v237
	v_mul_f32_e32 v176, v188, v176
	v_mul_f32_e32 v177, v189, v177
	v_mul_f32_e32 v178, v178, v180
	v_mul_f32_e32 v179, v179, v181
	v_mul_f32_e32 v176, v176, v158
	v_mul_f32_e32 v177, v177, v159
	v_mul_f32_e32 v180, v182, v180
	v_mul_f32_e32 v181, v183, v181
	v_mul_f32_e32 v158, v162, v158
	v_mul_f32_e32 v159, v163, v159
	v_cvt_pk_bf16_f32 v163, v180, v181
	v_cvt_pk_bf16_f32 v162, v158, v159
	v_cvt_pk_bf16_f32 v158, v176, v177
	v_cvt_pk_bf16_f32 v159, v178, v179
	ds_write_b64 v2, v[162:163] offset:21280
	ds_write_b64 v2, v[158:159] offset:23584

	ds_write_b64 v2, v[232:233] offset:18976
	ds_read_b128 v[192:195], v250 offset:17280
	ds_read_b128 v[184:187], v250 offset:17536
	ds_read_b128 v[180:183], v250 offset:17792
	ds_read_b128 v[176:179], v250 offset:18048
	s_waitcnt lgkmcnt(3)
	v_add_f32_e32 v172, v172, v192
	v_exp_f32_e32 v172, v172
	v_add_f32_e32 v173, v173, v193
	v_exp_f32_e32 v173, v173

	v_add_f32_e32 v172, 1.0, v172
	v_rcp_f32_e32 v172, v172
	v_add_f32_e32 v173, 1.0, v173
	v_rcp_f32_e32 v173, v173
	v_add_f32_e32 v174, v174, v194
	v_mul_f32_e32 v172, 0xbf60028a, v172
	v_exp_f32_e32 v172, v172
	v_exp_f32_e32 v174, v174

	v_add_f32_e32 v175, v175, v195

	v_mul_f32_dpp v172, v172, v172 row_shr:1 row_mask:0xf bank_mask:0xf

	v_add_f32_e32 v174, 1.0, v174
	v_rcp_f32_e32 v174, v174

	v_mul_f32_dpp v172, v172, v172 row_shr:2 row_mask:0xf bank_mask:0xf

	v_exp_f32_e32 v175, v175


	s_nop 0
	v_mul_f32_dpp v172, v172, v172 row_shr:4 row_mask:0xf bank_mask:0xf

	v_add_f32_e32 v175, 1.0, v175
	v_rcp_f32_e32 v175, v175

	v_mul_f32_dpp v172, v172, v172 row_shr:8 row_mask:0xf bank_mask:0xf
	v_mov_b32_e32 v232, v172
	v_mul_f32_e32 v172, 0xbf60028a, v173
	v_exp_f32_e32 v173, v172

	v_mov_b32_e32 v192, 1.0


	s_nop 0
	v_mul_f32_dpp v173, v173, v173 row_shr:1 row_mask:0xf bank_mask:0xf

	v_mov_b32_dpp v192, v232 row_shr:1 row_mask:0xf bank_mask:0xf
	s_nop 0

	v_mul_f32_dpp v173, v173, v173 row_shr:2 row_mask:0xf bank_mask:0xf

	s_nop 1

	v_mul_f32_dpp v173, v173, v173 row_shr:4 row_mask:0xf bank_mask:0xf

	s_nop 1

	v_mul_f32_dpp v173, v173, v173 row_shr:8 row_mask:0xf bank_mask:0xf
	v_mov_b32_e32 v233, v173
	v_mul_f32_e32 v173, 0xbf60028a, v174
	v_exp_f32_e32 v174, v173
	v_mov_b32_e32 v193, 1.0


	s_nop 0
	v_mul_f32_dpp v174, v174, v174 row_shr:1 row_mask:0xf bank_mask:0xf

	v_mov_b32_dpp v193, v233 row_shr:1 row_mask:0xf bank_mask:0xf
	s_nop 0

	v_mul_f32_dpp v174, v174, v174 row_shr:2 row_mask:0xf bank_mask:0xf

	s_nop 1

	v_mul_f32_dpp v174, v174, v174 row_shr:4 row_mask:0xf bank_mask:0xf

	s_nop 1

	v_mul_f32_dpp v174, v174, v174 row_shr:8 row_mask:0xf bank_mask:0xf
	v_mov_b32_e32 v236, v174
	v_mul_f32_e32 v174, 0xbf60028a, v175
	v_exp_f32_e32 v175, v174
	v_mov_b32_e32 v194, 1.0


	s_nop 0
	v_mul_f32_dpp v175, v175, v175 row_shr:1 row_mask:0xf bank_mask:0xf

	v_mov_b32_dpp v194, v236 row_shr:1 row_mask:0xf bank_mask:0xf
	s_nop 0

	v_mul_f32_dpp v175, v175, v175 row_shr:2 row_mask:0xf bank_mask:0xf

	s_nop 1

	v_mul_f32_dpp v175, v175, v175 row_shr:4 row_mask:0xf bank_mask:0xf

	s_nop 1

	v_mul_f32_dpp v175, v175, v175 row_shr:8 row_mask:0xf bank_mask:0xf
	v_mov_b32_e32 v237, v175
	v_mov_b32_e32 v195, 1.0
	s_nop 0

	s_nop 0
	v_mov_b32_dpp v195, v237 row_shr:1 row_mask:0xf bank_mask:0xf
	s_and_saveexec_b64 s[8:9], s[40:41]
	ds_write_b64 v247, v[232:233] offset:25984
	ds_write_b64 v247, v[236:237] offset:25992
	s_or_b64 exec, exec, s[8:9]
	s_waitcnt lgkmcnt(2)
	v_add_f32_e32 v170, v170, v186
	v_add_f32_e32 v168, v168, v184
	v_add_f32_e32 v169, v169, v185
	v_exp_f32_e32 v170, v170
	v_add_f32_e32 v171, v171, v187
	v_exp_f32_e32 v168, v168
	v_exp_f32_e32 v169, v169
	v_exp_f32_e32 v171, v171
	v_add_f32_e32 v170, 1.0, v170
	v_add_f32_e32 v168, 1.0, v168
	v_add_f32_e32 v169, 1.0, v169
	v_rcp_f32_e32 v172, v170
	v_add_f32_e32 v170, 1.0, v171
	v_rcp_f32_e32 v168, v168
	v_rcp_f32_e32 v169, v169
	v_rcp_f32_e32 v173, v170
	v_rcp_f32_e32 v174, v232
	v_rcp_f32_e32 v175, v233
	v_rcp_f32_e32 v184, v236
	v_rcp_f32_e32 v185, v237
	s_waitcnt lgkmcnt(1)
	v_mul_f32_e32 v170, v182, v224
	v_mul_f32_e32 v171, v183, v225
	v_mul_f32_e32 v180, v180, v222
	v_mul_f32_e32 v181, v181, v223
	v_mul_f32_e32 v186, v238, v170
	v_mul_f32_e32 v187, v239, v171
	v_mul_f32_e32 v170, v230, v180
	v_mul_f32_e32 v171, v231, v181
	v_add_f32_e32 v180, -1.0, v168
	v_add_f32_e32 v181, -1.0, v169
	v_add_f32_e32 v182, -1.0, v172
	v_add_f32_e32 v183, -1.0, v173
	s_waitcnt lgkmcnt(0)
	v_fma_f32 v176, v176, v180, 1.0
	v_fma_f32 v177, v177, v181, 1.0
	v_fma_f32 v178, v178, v182, 1.0
	v_fma_f32 v179, v179, v183, 1.0
	v_mul_f32_e32 v176, v176, v222
	v_mul_f32_e32 v177, v177, v223
	v_mul_f32_e32 v178, v178, v224
	v_mul_f32_e32 v179, v179, v225
	v_mul_f32_e32 v172, v186, v172
	v_mul_f32_e32 v173, v187, v173
	v_mul_f32_e32 v168, v170, v168
	v_mul_f32_e32 v169, v171, v169
	v_mul_f32_e32 v180, v172, v184
	v_mul_f32_e32 v181, v173, v185
	v_mul_f32_e32 v172, v168, v174
	v_mul_f32_e32 v173, v169, v175
	v_mul_f32_e32 v178, v178, v184
	v_mul_f32_e32 v179, v179, v185
	v_mul_f32_e32 v168, v176, v174
	v_mul_f32_e32 v169, v177, v175
	v_cvt_pk_bf16_f32 v172, v172, v173
	v_cvt_pk_bf16_f32 v168, v168, v169
	v_cvt_pk_bf16_f32 v169, v178, v179
	v_cvt_pk_bf16_f32 v173, v180, v181
	ds_write_b64 v2, v[168:169] offset:21312
	ds_write_b64 v2, v[172:173] offset:23616

	ds_write_b64 v2, v[148:149] offset:19008
	ds_read_b128 v[204:207], v250 offset:17344
	ds_read_b128 v[182:185], v250 offset:17600
	ds_read_b128 v[178:181], v250 offset:17856
	ds_read_b128 v[174:177], v250 offset:18112
	v_mov_b32_e32 v222, 1.0
	s_waitcnt lgkmcnt(3)
	v_add_f32_e32 v148, v164, v204
	v_exp_f32_e32 v148, v148
	v_add_f32_e32 v164, v166, v206
	v_add_f32_e32 v149, v165, v205
	v_exp_f32_e32 v164, v164
	v_add_f32_e32 v148, 1.0, v148
	v_rcp_f32_e32 v148, v148
	v_add_f32_e32 v165, v167, v207
	v_exp_f32_e32 v165, v165
	v_add_f32_e32 v164, 1.0, v164
	v_mul_f32_e32 v148, 0xbf60028a, v148
	v_exp_f32_e32 v148, v148
	v_exp_f32_e32 v149, v149
	v_rcp_f32_e32 v166, v164
	v_add_f32_e32 v164, 1.0, v165
	v_rcp_f32_e32 v167, v164

	v_add_f32_e32 v149, 1.0, v149
	v_rcp_f32_e32 v149, v149

	v_mul_f32_dpp v148, v148, v148 row_shr:1 row_mask:0xf bank_mask:0xf

	v_mov_b32_e32 v223, 1.0
	v_mov_b32_e32 v224, 1.0

	v_mul_f32_dpp v148, v148, v148 row_shr:2 row_mask:0xf bank_mask:0xf

	v_mov_b32_e32 v225, 1.0
	s_nop 0

	v_mul_f32_dpp v148, v148, v148 row_shr:4 row_mask:0xf bank_mask:0xf

	s_nop 1

	v_mul_f32_dpp v148, v148, v148 row_shr:8 row_mask:0xf bank_mask:0xf
	v_mov_b32_e32 v232, v148
	v_mul_f32_e32 v148, 0xbf60028a, v149
	v_exp_f32_e32 v148, v148

	v_mov_b32_dpp v222, v232 row_shr:1 row_mask:0xf bank_mask:0xf


	s_nop 0
	v_mul_f32_dpp v148, v148, v148 row_shr:1 row_mask:0xf bank_mask:0xf

	s_nop 1

	v_mul_f32_dpp v148, v148, v148 row_shr:2 row_mask:0xf bank_mask:0xf

	s_nop 1

	v_mul_f32_dpp v148, v148, v148 row_shr:4 row_mask:0xf bank_mask:0xf

	s_nop 1

	v_mul_f32_dpp v148, v148, v148 row_shr:8 row_mask:0xf bank_mask:0xf
	v_mov_b32_e32 v233, v148
	v_mul_f32_e32 v148, 0xbf60028a, v166
	v_exp_f32_e32 v148, v148

	v_mov_b32_dpp v223, v233 row_shr:1 row_mask:0xf bank_mask:0xf


	s_nop 0
	v_mul_f32_dpp v148, v148, v148 row_shr:1 row_mask:0xf bank_mask:0xf

	s_nop 1

	v_mul_f32_dpp v148, v148, v148 row_shr:2 row_mask:0xf bank_mask:0xf

	s_nop 1

	v_mul_f32_dpp v148, v148, v148 row_shr:4 row_mask:0xf bank_mask:0xf

	s_nop 1

	v_mul_f32_dpp v148, v148, v148 row_shr:8 row_mask:0xf bank_mask:0xf
	v_mov_b32_e32 v236, v148
	v_mul_f32_e32 v148, 0xbf60028a, v167
	v_exp_f32_e32 v148, v148

	v_mov_b32_dpp v224, v236 row_shr:1 row_mask:0xf bank_mask:0xf


	s_nop 0
	v_mul_f32_dpp v148, v148, v148 row_shr:1 row_mask:0xf bank_mask:0xf

	s_nop 1

	v_mul_f32_dpp v148, v148, v148 row_shr:2 row_mask:0xf bank_mask:0xf

	s_nop 1

	v_mul_f32_dpp v148, v148, v148 row_shr:4 row_mask:0xf bank_mask:0xf

	s_nop 1

	v_mul_f32_dpp v148, v148, v148 row_shr:8 row_mask:0xf bank_mask:0xf
	v_mov_b32_e32 v237, v148
	s_nop 1
	v_mov_b32_dpp v225, v237 row_shr:1 row_mask:0xf bank_mask:0xf

	s_and_saveexec_b64 s[8:9], s[40:41]
	s_cbranch_execz .LBB0_327
	ds_write_b64 v247, v[232:233] offset:26048
	ds_write_b64 v247, v[236:237] offset:26056
	s_branch .LBB0_327

.LBB0_538:
	v_mbcnt_lo_u32_b32 v238, -1, 0
	v_mbcnt_hi_u32_b32 v238, -1, v238
	s_cmpk_lg_i32 s55, 0x100
	v_and_b32_e32 v239, 63, v238
	v_lshl_add_u32 v150, v239, 4, 0
	ds_read_b128 v[80:83], v150
	s_waitcnt vmcnt(32)
	ds_read_b128 v[88:91], v150 offset:1024
	ds_read_b128 v[92:95], v150 offset:8192
	ds_read_b128 v[96:99], v150 offset:9216
	s_cselect_b32 s34, s55, 0xf0
	v_and_b32_e32 v237, 15, v238
	s_add_i32 s34, s34, s52
	s_waitcnt vmcnt(1) lgkmcnt(3)
	v_mfma_f32_16x16x32_bf16 v[80:83], v[80:83], v[76:79], 0
	v_or_b32_e32 v2, s34, v237
	v_bfe_u32 v246, v238, 4, 2
	v_mov_b64_e32 v[142:143], v[162:163]
	s_waitcnt lgkmcnt(2)
	v_mfma_f32_16x16x32_bf16 v[120:123], v[88:91], v[72:75], v[80:83]
	ds_read_b128 v[88:91], v150 offset:2048
	v_mov_b64_e32 v[144:145], v[160:161]
	v_mov_b64_e32 v[146:147], v[156:157]
	v_xad_u32 v80, v2, -1, s58
	v_cndmask_b32_e64 v2, v80, v2, s[38:39]
	s_waitcnt lgkmcnt(2)
	v_mfma_f32_16x16x32_bf16 v[80:83], v[92:95], v[68:71], 0
	v_add_u32_e32 v2, s53, v2
	v_mov_b64_e32 v[92:93], s[4:5]
	v_mad_i64_i32 v[126:127], s[34:35], v2, s62, v[92:93]
	s_waitcnt vmcnt(0) lgkmcnt(1)
	v_mfma_f32_16x16x32_bf16 v[100:103], v[96:99], v[84:87], v[80:83]
	ds_read_b128 v[92:95], v150 offset:10240
	v_lshlrev_b32_e32 v2, 3, v246
	v_lshl_add_u64 v[96:97], v[152:153], 1, v[126:127]
	ds_read_b128 v[80:83], v150 offset:3072
	s_waitcnt lgkmcnt(2)
	v_mfma_f32_16x16x32_bf16 v[88:91], v[88:91], v[76:79], 0
	v_lshl_add_u64 v[96:97], v[96:97], 0, v[2:3]
	v_lshl_add_u64 v[98:99], v[96:97], 0, s[22:23]
	v_lshl_add_u64 v[108:109], v[96:97], 0, s[16:17]
	s_waitcnt lgkmcnt(0)
	v_mfma_f32_16x16x32_bf16 v[116:119], v[80:83], v[72:75], v[88:91]
	ds_read_b128 v[80:83], v150 offset:11264
	v_add_co_u32_e32 v130, vcc, s31, v96
	v_mfma_f32_16x16x32_bf16 v[88:91], v[92:95], v[68:71], 0
	ds_read_b128 v[92:95], v150 offset:4096
	v_addc_co_u32_e32 v131, vcc, 0, v97, vcc
	s_waitcnt lgkmcnt(1)
	v_mfma_f32_16x16x32_bf16 v[112:115], v[80:83], v[84:87], v[88:91]
	ds_read_b128 v[80:83], v150 offset:5120
	s_nop 2
	ds_read_b128 v[88:91], v150 offset:12288
	global_load_dwordx2 v[156:157], v[98:99], off offset:32
	global_load_dwordx2 v[164:165], v[108:109], off offset:32
	global_load_dwordx2 v[160:161], v[98:99], off offset:64
	global_load_dwordx2 v[162:163], v[98:99], off offset:96
	s_waitcnt lgkmcnt(2)
	v_mfma_f32_16x16x32_bf16 v[92:95], v[92:95], v[76:79], 0
	ds_read_b128 v[104:107], v150 offset:13312
	v_lshl_add_u64 v[110:111], v[96:97], 0, s[14:15]
	v_add_co_u32_e32 v148, vcc, s19, v96
	global_load_dwordx2 v[170:171], v[110:111], off offset:32
	global_load_dwordx2 v[166:167], v[108:109], off offset:64
	global_load_dwordx2 v[172:173], v[110:111], off offset:64
	global_load_dwordx2 v[168:169], v[108:109], off offset:96
	v_addc_co_u32_e32 v149, vcc, 0, v97, vcc
	s_waitcnt lgkmcnt(2)
	v_mfma_f32_16x16x32_bf16 v[96:99], v[80:83], v[72:75], v[92:95]
	v_mov_b64_e32 v[128:129], v[158:159]
	v_and_b32_e32 v188, 48, v238
	v_mov_b32_e32 v189, v3
	s_waitcnt lgkmcnt(1)
	v_mfma_f32_16x16x32_bf16 v[80:83], v[88:91], v[68:71], 0
	ds_read_b128 v[88:91], v150 offset:6144
	global_load_dwordx2 v[158:159], v[130:131], off offset:2048
	global_load_dwordx2 v[174:175], v[148:149], off
	global_load_dwordx2 v[178:179], v[130:131], off
	global_load_dwordx2 v[176:177], v[110:111], off offset:96
	ds_read_b128 v[108:111], v150 offset:7168
	s_waitcnt lgkmcnt(2)
	v_mfma_f32_16x16x32_bf16 v[92:95], v[104:107], v[84:87], v[80:83]
	v_lshl_add_u64 v[104:105], v[126:127], 0, s[96:97]
	v_lshl_add_u64 v[104:105], v[104:105], 0, v[188:189]
	v_add_u32_e32 v247, 0, v188
	ds_read_b128 v[80:83], v150 offset:14336
	s_waitcnt lgkmcnt(2)
	v_mfma_f32_16x16x32_bf16 v[76:79], v[88:91], v[76:79], 0
	v_lshl_add_u64 v[148:149], v[104:105], 0, s[24:25]
	v_lshlrev_b32_e32 v126, 16, v128
	v_and_b32_e32 v127, 0xffff0000, v128
	s_waitcnt lgkmcnt(1)
	v_mfma_f32_16x16x32_bf16 v[88:91], v[108:111], v[72:75], v[76:79]
	ds_read_b128 v[72:75], v247 offset:17728
	v_lshlrev_b32_e32 v128, 16, v129
	v_and_b32_e32 v129, 0xffff0000, v129
	v_add_co_u32_e32 v76, vcc, s64, v104
	s_waitcnt lgkmcnt(1)
	v_mfma_f32_16x16x32_bf16 v[108:111], v[80:83], v[68:71], 0
	v_addc_co_u32_e32 v77, vcc, 0, v105, vcc
	ds_read_b128 v[104:107], v150 offset:15360
	ds_read_b128 v[68:71], v247 offset:17664
	v_lshlrev_b32_e32 v216, 16, v146
	v_and_b32_e32 v217, 0xffff0000, v146
	v_lshlrev_b32_e32 v218, 16, v147
	v_and_b32_e32 v219, 0xffff0000, v147
	s_waitcnt lgkmcnt(0)
	v_mul_f32_e32 v130, v70, v128
	v_mul_f32_e32 v131, v71, v129
	v_mul_f32_e32 v184, v68, v126
	v_mul_f32_e32 v185, v69, v127
	v_mul_f32_e32 v68, v74, v218
	v_mul_f32_e32 v69, v75, v219
	v_mul_f32_e32 v70, v72, v216
	v_mul_f32_e32 v71, v73, v217
	v_mul_f32_e32 v68, v68, v68
	v_mul_f32_e32 v69, v69, v69
	v_mul_f32_e32 v70, v70, v70
	v_mul_f32_e32 v71, v71, v71
	v_fma_f32 v78, v130, v130, v68
	v_fma_f32 v79, v131, v131, v69
	v_fma_f32 v80, v184, v184, v70
	v_fma_f32 v81, v185, v185, v71
	ds_read_b128 v[68:71], v247 offset:17792
	ds_read_b128 v[72:75], v247 offset:17856
	v_lshlrev_b32_e32 v196, 16, v144
	v_and_b32_e32 v197, 0xffff0000, v144
	v_lshlrev_b32_e32 v198, 16, v145
	v_and_b32_e32 v199, 0xffff0000, v145
	s_waitcnt lgkmcnt(1)
	v_mul_f32_e32 v70, v70, v198
	v_mul_f32_e32 v71, v71, v199
	v_mul_f32_e32 v68, v68, v196
	v_mul_f32_e32 v69, v69, v197
	v_lshlrev_b32_e32 v150, 16, v142
	v_and_b32_e32 v151, 0xffff0000, v142
	v_lshlrev_b32_e32 v180, 16, v143
	v_and_b32_e32 v181, 0xffff0000, v143
	v_fma_f32 v70, v70, v70, v78
	v_fma_f32 v71, v71, v71, v79
	v_fma_f32 v68, v68, v68, v80
	v_fma_f32 v69, v69, v69, v81
	s_waitcnt lgkmcnt(0)
	v_mul_f32_e32 v74, v74, v180
	v_mul_f32_e32 v75, v75, v181
	v_mul_f32_e32 v72, v72, v150
	v_mul_f32_e32 v73, v73, v151
	v_fma_f32 v70, v74, v74, v70
	v_fma_f32 v71, v75, v75, v71
	v_fma_f32 v68, v72, v72, v68
	v_fma_f32 v69, v73, v73, v69
	v_lshlrev_b32_e32 v143, 2, v239
	v_pk_mov_b32 v[72:73], v[68:69], v[70:71] op_sel:[1,0]
	v_mov_b32_e32 v69, v71
	v_add_f32_e32 v68, v72, v68
	v_add_f32_e32 v69, v73, v69
	v_xor_b32_e32 v248, 64, v143
	v_add_f32_e32 v142, v68, v69
	global_load_dwordx4 v[68:71], v[148:149], off offset:256
	global_load_dwordx4 v[72:75], v[148:149], off offset:64
	s_nop 0
	global_load_dwordx4 v[76:79], v[76:77], off
	s_nop 0
	global_load_dwordx4 v[80:83], v[148:149], off offset:320
	ds_bpermute_b32 v144, v248, v142
	v_xor_b32_e32 v249, 0x80, v143
	v_mfma_f32_16x16x32_bf16 v[84:87], v[104:107], v[84:87], v[108:111]
	v_mov_b32_e32 v146, 1.0
	v_mov_b32_e32 v147, 1.0
	s_waitcnt lgkmcnt(0)
	v_add_f32_e32 v186, v142, v144
	ds_read_b128 v[142:145], v247 offset:17152
	ds_bpermute_b32 v187, v249, v186
	ds_read_b128 v[108:111], v247 offset:17408
	ds_read_b128 v[104:107], v247 offset:17920
	v_mov_b32_e32 v148, 1.0
	v_mov_b32_e32 v149, 1.0
	s_waitcnt lgkmcnt(3)
	v_add_f32_e32 v120, v120, v142
	v_add_f32_e32 v121, v121, v143
	v_exp_f32_e32 v120, v120
	v_exp_f32_e32 v121, v121
	v_add_f32_e32 v122, v122, v144
	v_exp_f32_e32 v122, v122
	v_add_f32_e32 v120, 1.0, v120
	v_add_f32_e32 v121, 1.0, v121
	v_rcp_f32_e32 v120, v120
	v_rcp_f32_e32 v121, v121
	v_add_f32_e32 v123, v123, v145
	v_exp_f32_e32 v123, v123
	v_mul_f32_e32 v120, 0xbf60028a, v120
	v_mul_f32_e32 v121, 0xbf60028a, v121
	v_exp_f32_e32 v120, v120
	v_exp_f32_e32 v121, v121
	v_add_f32_e32 v122, 1.0, v122
	v_rcp_f32_e32 v144, v122
	v_add_f32_e32 v122, 1.0, v123
	v_rcp_f32_e32 v145, v122


	v_cmp_eq_u32_e64 s[40:41], 15, v237


	v_mul_f32_dpp v120, v120, v120 row_shr:1 row_mask:0xf bank_mask:0xf
	v_mul_f32_dpp v121, v121, v121 row_shr:1 row_mask:0xf bank_mask:0xf


	v_add_u32_e32 v236, s33, v188


	v_mul_f32_dpp v120, v120, v120 row_shr:2 row_mask:0xf bank_mask:0xf
	v_mul_f32_dpp v121, v121, v121 row_shr:2 row_mask:0xf bank_mask:0xf


	s_nop 0


	v_mul_f32_dpp v120, v120, v120 row_shr:4 row_mask:0xf bank_mask:0xf
	v_mul_f32_dpp v121, v121, v121 row_shr:4 row_mask:0xf bank_mask:0xf


	s_nop 0


	v_mul_f32_dpp v120, v120, v120 row_shr:8 row_mask:0xf bank_mask:0xf
	v_mul_f32_dpp v121, v121, v121 row_shr:8 row_mask:0xf bank_mask:0xf
	v_mov_b64_e32 v[142:143], v[120:121]
	v_mul_f32_e32 v122, 0xbf60028a, v144
	v_mul_f32_e32 v123, 0xbf60028a, v145
	v_exp_f32_e32 v122, v122
	v_exp_f32_e32 v123, v123


	v_mov_b32_dpp v146, v142 row_shr:1 row_mask:0xf bank_mask:0xf


	v_mul_f32_dpp v122, v122, v122 row_shr:1 row_mask:0xf bank_mask:0xf
	v_mul_f32_dpp v123, v123, v123 row_shr:1 row_mask:0xf bank_mask:0xf


	s_nop 0
	v_mul_f32_dpp v122, v122, v122 row_shr:2 row_mask:0xf bank_mask:0xf
	v_mul_f32_dpp v123, v123, v123 row_shr:2 row_mask:0xf bank_mask:0xf


	v_mov_b32_dpp v147, v143 row_shr:1 row_mask:0xf bank_mask:0xf


	v_mul_f32_dpp v122, v122, v122 row_shr:4 row_mask:0xf bank_mask:0xf
	v_mul_f32_dpp v123, v123, v123 row_shr:4 row_mask:0xf bank_mask:0xf


	s_nop 0
	v_mul_f32_dpp v122, v122, v122 row_shr:8 row_mask:0xf bank_mask:0xf
	v_mul_f32_dpp v123, v123, v123 row_shr:8 row_mask:0xf bank_mask:0xf
	v_mov_b64_e32 v[144:145], v[122:123]
	s_nop 1
	v_mov_b32_dpp v148, v144 row_shr:1 row_mask:0xf bank_mask:0xf

	v_mov_b32_dpp v149, v145 row_shr:1 row_mask:0xf bank_mask:0xf

	s_and_saveexec_b64 s[34:35], s[40:41]
	ds_write_b128 v236, v[142:145] offset:25856
	s_or_b64 exec, exec, s[34:35]
	s_waitcnt lgkmcnt(2)
	v_add_f32_e32 v120, v186, v187
	v_mul_f32_e32 v121, 0x4f800000, v120
	v_cmp_gt_f32_e32 vcc, s69, v120
	s_waitcnt lgkmcnt(1)
	v_add_f32_e32 v100, v100, v108
	v_add_f32_e32 v101, v101, v109
	v_cndmask_b32_e32 v120, v120, v121, vcc
	v_sqrt_f32_e32 v121, v120
	v_add_f32_e32 v102, v102, v110
	v_add_f32_e32 v103, v103, v111
	v_exp_f32_e32 v100, v100
	v_add_u32_e32 v122, -1, v121
	v_fma_f32 v186, -v122, v121, v120
	v_add_u32_e32 v123, 1, v121
	v_cmp_ge_f32_e64 s[42:43], 0, v186
	v_exp_f32_e32 v101, v101
	v_exp_f32_e32 v102, v102
	v_cndmask_b32_e64 v122, v121, v122, s[42:43]
	v_fma_f32 v121, -v123, v121, v120
	v_cmp_lt_f32_e64 s[42:43], 0, v121
	v_exp_f32_e32 v103, v103
	v_add_f32_e32 v100, 1.0, v100
	v_cndmask_b32_e64 v121, v122, v123, s[42:43]
	v_mul_f32_e32 v122, 0x37800000, v121
	v_cndmask_b32_e32 v121, v121, v122, vcc
	v_cmp_class_f32_e32 vcc, v120, v242
	v_add_f32_e32 v101, 1.0, v101
	v_add_f32_e32 v102, 1.0, v102
	v_cndmask_b32_e32 v120, v121, v120, vcc
	v_max_f32_e32 v120, 0x2b8cbccc, v120
	v_div_scale_f32 v121, s[34:35], v120, v120, 1.0
	v_rcp_f32_e32 v122, v121
	v_add_f32_e32 v103, 1.0, v103
	v_rcp_f32_e32 v100, v100
	v_rcp_f32_e32 v101, v101
	v_fma_f32 v123, -v121, v122, 1.0
	v_fmac_f32_e32 v122, v123, v122
	v_div_scale_f32 v123, vcc, 1.0, v120, 1.0
	v_mul_f32_e32 v186, v123, v122
	v_fma_f32 v187, -v121, v186, v123
	v_rcp_f32_e32 v102, v102
	v_rcp_f32_e32 v103, v103
	v_fmac_f32_e32 v186, v187, v122
	v_fma_f32 v121, -v121, v186, v123
	v_div_fmas_f32 v121, v121, v122, v186
	v_rcp_f32_e32 v108, v142
	v_rcp_f32_e32 v109, v143
	v_rcp_f32_e32 v110, v144
	v_rcp_f32_e32 v111, v145
	v_div_fixup_f32 v194, v121, v120, 1.0
	v_add_f32_e32 v120, -1.0, v102
	v_add_f32_e32 v121, -1.0, v103
	v_add_f32_e32 v122, -1.0, v100
	v_add_f32_e32 v123, -1.0, v101
	s_waitcnt lgkmcnt(0)
	v_fma_f32 v106, v106, v120, 1.0
	v_fma_f32 v107, v107, v121, 1.0
	v_fma_f32 v104, v104, v122, 1.0
	v_fma_f32 v105, v105, v123, 1.0
	v_mul_f32_e32 v186, v130, v194
	v_mul_f32_e32 v187, v131, v194
	v_mul_f32_e32 v184, v184, v194
	v_mul_f32_e32 v185, v185, v194
	v_mul_f32_e32 v214, v106, v128
	v_mul_f32_e32 v215, v107, v129
	v_mul_f32_e32 v212, v104, v126
	v_mul_f32_e32 v213, v105, v127
	v_mad_u32_u24 v2, v237, s63, v2
	v_mul_f32_e32 v100, v100, v184
	v_mul_f32_e32 v101, v101, v185
	v_mul_f32_e32 v102, v102, v186
	v_mul_f32_e32 v103, v103, v187
	v_mul_f32_e32 v106, v214, v110
	v_mul_f32_e32 v107, v215, v111
	v_mul_f32_e32 v104, v212, v108
	v_mul_f32_e32 v105, v213, v109
	v_mul_f32_e32 v102, v102, v110
	v_mul_f32_e32 v103, v103, v111
	v_mul_f32_e32 v100, v100, v108
	v_mul_f32_e32 v101, v101, v109
	v_cvt_pk_bf16_f32 v104, v104, v105
	v_cvt_pk_bf16_f32 v105, v106, v107
	v_add_u32_e32 v2, s33, v2
	v_cvt_pk_bf16_f32 v100, v100, v101
	v_cvt_pk_bf16_f32 v101, v102, v103
	ds_write_b64 v2, v[104:105] offset:21248
	ds_write_b64 v2, v[100:101] offset:23552
	ds_read_b128 v[108:111], v247 offset:18176
	ds_write_b64 v2, v[124:125] offset:18944
	ds_read_b128 v[188:191], v247 offset:17216
	ds_read_b128 v[128:131], v247 offset:17472
	ds_read_b128 v[124:127], v247 offset:17728
	ds_read_b128 v[120:123], v247 offset:17984
	v_mov_b32_e32 v192, 1.0
	s_waitcnt lgkmcnt(3)
	v_add_f32_e32 v102, v116, v188
	v_add_f32_e32 v103, v117, v189
	v_exp_f32_e32 v102, v102
	v_exp_f32_e32 v103, v103
	v_add_f32_e32 v106, v118, v190
	v_exp_f32_e32 v106, v106
	v_add_f32_e32 v102, 1.0, v102
	v_add_f32_e32 v103, 1.0, v103
	v_rcp_f32_e32 v102, v102
	v_rcp_f32_e32 v103, v103
	v_add_f32_e32 v107, v119, v191
	v_exp_f32_e32 v107, v107
	v_mul_f32_e32 v102, 0xbf60028a, v102
	v_mul_f32_e32 v103, 0xbf60028a, v103
	v_exp_f32_e32 v102, v102
	v_exp_f32_e32 v103, v103
	v_add_f32_e32 v106, 1.0, v106
	v_rcp_f32_e32 v118, v106
	v_add_f32_e32 v106, 1.0, v107
	v_rcp_f32_e32 v119, v106


	v_mov_b32_e32 v193, 1.0


	v_mul_f32_dpp v102, v102, v102 row_shr:1 row_mask:0xf bank_mask:0xf
	v_mul_f32_dpp v103, v103, v103 row_shr:1 row_mask:0xf bank_mask:0xf


	v_mov_b32_e32 v208, 1.0


	v_mul_f32_dpp v102, v102, v102 row_shr:2 row_mask:0xf bank_mask:0xf
	v_mul_f32_dpp v103, v103, v103 row_shr:2 row_mask:0xf bank_mask:0xf


	v_mov_b32_e32 v209, 1.0


	v_mul_f32_dpp v102, v102, v102 row_shr:4 row_mask:0xf bank_mask:0xf
	v_mul_f32_dpp v103, v103, v103 row_shr:4 row_mask:0xf bank_mask:0xf


	s_nop 0


	v_mul_f32_dpp v102, v102, v102 row_shr:8 row_mask:0xf bank_mask:0xf
	v_mul_f32_dpp v103, v103, v103 row_shr:8 row_mask:0xf bank_mask:0xf
	v_mov_b64_e32 v[188:189], v[102:103]
	v_mul_f32_e32 v102, 0xbf60028a, v118
	v_mul_f32_e32 v103, 0xbf60028a, v119
	v_exp_f32_e32 v102, v102
	v_exp_f32_e32 v103, v103


	v_mov_b32_dpp v192, v188 row_shr:1 row_mask:0xf bank_mask:0xf


	v_mul_f32_dpp v102, v102, v102 row_shr:1 row_mask:0xf bank_mask:0xf
	v_mul_f32_dpp v103, v103, v103 row_shr:1 row_mask:0xf bank_mask:0xf


	s_nop 0
	v_mul_f32_dpp v102, v102, v102 row_shr:2 row_mask:0xf bank_mask:0xf
	v_mul_f32_dpp v103, v103, v103 row_shr:2 row_mask:0xf bank_mask:0xf


	v_mov_b32_dpp v193, v189 row_shr:1 row_mask:0xf bank_mask:0xf


	v_mul_f32_dpp v102, v102, v102 row_shr:4 row_mask:0xf bank_mask:0xf
	v_mul_f32_dpp v103, v103, v103 row_shr:4 row_mask:0xf bank_mask:0xf


	s_nop 0
	v_mul_f32_dpp v102, v102, v102 row_shr:8 row_mask:0xf bank_mask:0xf
	v_mul_f32_dpp v103, v103, v103 row_shr:8 row_mask:0xf bank_mask:0xf
	v_mov_b64_e32 v[190:191], v[102:103]
	s_nop 1
	v_mov_b32_dpp v208, v190 row_shr:1 row_mask:0xf bank_mask:0xf

	v_mov_b32_dpp v209, v191 row_shr:1 row_mask:0xf bank_mask:0xf

	s_and_saveexec_b64 s[34:35], s[40:41]
	ds_write_b128 v236, v[188:191] offset:25920
	s_or_b64 exec, exec, s[34:35]
	s_waitcnt lgkmcnt(2)
	v_add_f32_e32 v102, v112, v128
	v_add_f32_e32 v103, v113, v129
	v_add_f32_e32 v106, v114, v130
	v_add_f32_e32 v107, v115, v131
	v_exp_f32_e32 v102, v102
	v_exp_f32_e32 v103, v103
	v_exp_f32_e32 v106, v106
	v_exp_f32_e32 v107, v107
	v_add_f32_e32 v102, 1.0, v102
	v_add_f32_e32 v103, 1.0, v103
	v_add_f32_e32 v106, 1.0, v106
	v_add_f32_e32 v107, 1.0, v107
	v_rcp_f32_e32 v102, v102
	v_rcp_f32_e32 v103, v103
	v_rcp_f32_e32 v106, v106
	v_rcp_f32_e32 v107, v107
	v_mov_b32_e32 v195, v194
	v_rcp_f32_e32 v112, v188
	v_rcp_f32_e32 v113, v189
	v_rcp_f32_e32 v114, v190
	v_rcp_f32_e32 v115, v191
	s_waitcnt lgkmcnt(1)
	v_mul_f32_e32 v118, v126, v218
	v_mul_f32_e32 v119, v127, v219
	v_mul_f32_e32 v124, v124, v216
	v_mul_f32_e32 v125, v125, v217
	v_mov_b32_e32 v116, v194
	v_mov_b32_e32 v117, v194
	v_mul_f32_e32 v210, v116, v118
	v_mul_f32_e32 v211, v117, v119
	v_mul_f32_e32 v130, v194, v124
	v_mul_f32_e32 v131, v195, v125
	v_add_f32_e32 v118, -1.0, v106
	v_add_f32_e32 v119, -1.0, v107
	v_add_f32_e32 v124, -1.0, v102
	v_add_f32_e32 v125, -1.0, v103
	s_waitcnt lgkmcnt(0)
	v_fma_f32 v118, v122, v118, 1.0
	v_fma_f32 v119, v123, v119, 1.0
	v_fma_f32 v120, v120, v124, 1.0
	v_fma_f32 v121, v121, v125, 1.0
	v_mul_f32_e32 v226, v118, v218
	v_mul_f32_e32 v227, v119, v219
	v_mul_f32_e32 v228, v120, v216
	v_mul_f32_e32 v229, v121, v217
	v_mul_f32_e32 v106, v210, v106
	v_mul_f32_e32 v107, v211, v107
	v_mul_f32_e32 v102, v130, v102
	v_mul_f32_e32 v103, v131, v103
	v_mul_f32_e32 v118, v106, v114
	v_mul_f32_e32 v119, v107, v115
	v_mul_f32_e32 v114, v226, v114
	v_mul_f32_e32 v115, v227, v115
	v_mul_f32_e32 v106, v228, v112
	v_mul_f32_e32 v107, v229, v113
	v_mul_f32_e32 v102, v102, v112
	v_mul_f32_e32 v103, v103, v113
	v_cvt_pk_bf16_f32 v106, v106, v107
	v_cvt_pk_bf16_f32 v107, v114, v115
	v_cvt_pk_bf16_f32 v102, v102, v103
	v_cvt_pk_bf16_f32 v103, v118, v119
	ds_write_b64 v2, v[106:107] offset:21280
	ds_write_b64 v2, v[102:103] offset:23584
	ds_read_b128 v[118:121], v247 offset:18240
	ds_write_b64 v2, v[182:183] offset:18976
	ds_read_b128 v[204:207], v247 offset:17280
	ds_read_b128 v[126:129], v247 offset:17536
	ds_read_b128 v[122:125], v247 offset:17792
	ds_read_b128 v[112:115], v247 offset:18048
	v_mov_b32_e32 v216, 1.0
	s_waitcnt lgkmcnt(3)
	v_add_f32_e32 v96, v96, v204
	v_add_f32_e32 v97, v97, v205
	v_exp_f32_e32 v96, v96
	v_exp_f32_e32 v97, v97
	v_add_f32_e32 v98, v98, v206
	v_exp_f32_e32 v98, v98
	v_add_f32_e32 v96, 1.0, v96
	v_add_f32_e32 v97, 1.0, v97
	v_rcp_f32_e32 v96, v96
	v_rcp_f32_e32 v97, v97
	v_add_f32_e32 v99, v99, v207
	v_exp_f32_e32 v99, v99
	v_mul_f32_e32 v96, 0xbf60028a, v96
	v_mul_f32_e32 v97, 0xbf60028a, v97
	v_exp_f32_e32 v96, v96
	v_exp_f32_e32 v97, v97
	v_add_f32_e32 v98, 1.0, v98
	v_rcp_f32_e32 v200, v98
	v_add_f32_e32 v98, 1.0, v99
	v_rcp_f32_e32 v201, v98


	v_mov_b32_e32 v217, 1.0


	v_mul_f32_dpp v96, v96, v96 row_shr:1 row_mask:0xf bank_mask:0xf
	v_mul_f32_dpp v97, v97, v97 row_shr:1 row_mask:0xf bank_mask:0xf


	v_mov_b32_e32 v222, 1.0


	v_mul_f32_dpp v96, v96, v96 row_shr:2 row_mask:0xf bank_mask:0xf
	v_mul_f32_dpp v97, v97, v97 row_shr:2 row_mask:0xf bank_mask:0xf


	v_mov_b32_e32 v223, 1.0


	v_mul_f32_dpp v96, v96, v96 row_shr:4 row_mask:0xf bank_mask:0xf
	v_mul_f32_dpp v97, v97, v97 row_shr:4 row_mask:0xf bank_mask:0xf


	s_nop 0


	v_mul_f32_dpp v96, v96, v96 row_shr:8 row_mask:0xf bank_mask:0xf
	v_mul_f32_dpp v97, v97, v97 row_shr:8 row_mask:0xf bank_mask:0xf
	v_mov_b64_e32 v[182:183], v[96:97]
	v_mul_f32_e32 v98, 0xbf60028a, v200
	v_mul_f32_e32 v99, 0xbf60028a, v201
	v_exp_f32_e32 v98, v98
	v_exp_f32_e32 v99, v99


	v_mov_b32_dpp v216, v182 row_shr:1 row_mask:0xf bank_mask:0xf


	v_mul_f32_dpp v98, v98, v98 row_shr:1 row_mask:0xf bank_mask:0xf
	v_mul_f32_dpp v99, v99, v99 row_shr:1 row_mask:0xf bank_mask:0xf


	s_nop 0
	v_mul_f32_dpp v98, v98, v98 row_shr:2 row_mask:0xf bank_mask:0xf
	v_mul_f32_dpp v99, v99, v99 row_shr:2 row_mask:0xf bank_mask:0xf


	v_mov_b32_dpp v217, v183 row_shr:1 row_mask:0xf bank_mask:0xf


	v_mul_f32_dpp v98, v98, v98 row_shr:4 row_mask:0xf bank_mask:0xf
	v_mul_f32_dpp v99, v99, v99 row_shr:4 row_mask:0xf bank_mask:0xf


	s_nop 0
	v_mul_f32_dpp v98, v98, v98 row_shr:8 row_mask:0xf bank_mask:0xf
	v_mul_f32_dpp v99, v99, v99 row_shr:8 row_mask:0xf bank_mask:0xf
	v_mov_b64_e32 v[218:219], v[98:99]
	s_nop 1
	v_mov_b32_dpp v222, v218 row_shr:1 row_mask:0xf bank_mask:0xf

	v_mov_b32_dpp v223, v219 row_shr:1 row_mask:0xf bank_mask:0xf

	s_and_saveexec_b64 s[34:35], s[40:41]
	ds_write_b64 v236, v[182:183] offset:25984
	ds_write_b64 v236, v[218:219] offset:25992
	s_or_b64 exec, exec, s[34:35]
	s_waitcnt lgkmcnt(2)
	v_add_f32_e32 v92, v92, v126
	v_add_f32_e32 v93, v93, v127
	v_add_f32_e32 v94, v94, v128
	v_add_f32_e32 v95, v95, v129
	v_exp_f32_e32 v92, v92
	v_exp_f32_e32 v93, v93
	v_exp_f32_e32 v94, v94
	v_exp_f32_e32 v95, v95
	v_add_f32_e32 v92, 1.0, v92
	v_add_f32_e32 v93, 1.0, v93
	v_add_f32_e32 v94, 1.0, v94
	v_add_f32_e32 v95, 1.0, v95
	v_rcp_f32_e32 v92, v92
	v_rcp_f32_e32 v93, v93
	v_rcp_f32_e32 v94, v94
	v_rcp_f32_e32 v95, v95
	v_rcp_f32_e32 v96, v182
	v_rcp_f32_e32 v97, v183
	v_rcp_f32_e32 v98, v218
	v_rcp_f32_e32 v99, v219
	s_waitcnt lgkmcnt(1)
	v_mul_f32_e32 v124, v124, v198
	v_mul_f32_e32 v125, v125, v199
	v_mul_f32_e32 v122, v122, v196
	v_mul_f32_e32 v123, v123, v197
	v_mul_f32_e32 v224, v116, v124
	v_mul_f32_e32 v225, v117, v125
	v_mul_f32_e32 v220, v194, v122
	v_mul_f32_e32 v221, v195, v123
	v_add_f32_e32 v116, -1.0, v94
	v_add_f32_e32 v117, -1.0, v95
	v_add_f32_e32 v122, -1.0, v92
	v_add_f32_e32 v123, -1.0, v93
	s_waitcnt lgkmcnt(0)
	v_fma_f32 v114, v114, v116, 1.0
	v_fma_f32 v115, v115, v117, 1.0
	v_fma_f32 v112, v112, v122, 1.0
	v_fma_f32 v113, v113, v123, 1.0
	v_mul_f32_e32 v234, v114, v198
	v_mul_f32_e32 v235, v115, v199
	v_mul_f32_e32 v114, v112, v196
	v_mul_f32_e32 v115, v113, v197
	v_mul_f32_e32 v94, v224, v94
	v_mul_f32_e32 v95, v225, v95
	v_mul_f32_e32 v92, v220, v92
	v_mul_f32_e32 v93, v221, v93
	v_mul_f32_e32 v94, v94, v98
	v_mul_f32_e32 v95, v95, v99
	v_mul_f32_e32 v92, v92, v96
	v_mul_f32_e32 v93, v93, v97
	v_mul_f32_e32 v98, v234, v98
	v_mul_f32_e32 v99, v235, v99
	v_mul_f32_e32 v96, v114, v96
	v_mul_f32_e32 v97, v115, v97
	v_cvt_pk_bf16_f32 v117, v98, v99
	v_cvt_pk_bf16_f32 v116, v96, v97
	v_cvt_pk_bf16_f32 v112, v92, v93
	v_cvt_pk_bf16_f32 v113, v94, v95
	ds_write_b64 v2, v[116:117] offset:21312
	ds_write_b64 v2, v[112:113] offset:23616
	ds_read_b128 v[126:129], v247 offset:18304
	ds_write_b64 v2, v[140:141] offset:19008
	ds_read_b128 v[196:199], v247 offset:17344
	ds_read_b128 v[122:125], v247 offset:17600
	ds_read_b128 v[96:99], v247 offset:17856
	ds_read_b128 v[92:95], v247 offset:18112
	v_mov_b32_e32 v232, 1.0
	s_waitcnt lgkmcnt(3)
	v_add_f32_e32 v88, v88, v196
	v_add_f32_e32 v89, v89, v197
	v_exp_f32_e32 v88, v88
	v_exp_f32_e32 v89, v89
	v_add_f32_e32 v90, v90, v198
	v_exp_f32_e32 v90, v90
	v_add_f32_e32 v88, 1.0, v88
	v_add_f32_e32 v89, 1.0, v89
	v_rcp_f32_e32 v88, v88
	v_rcp_f32_e32 v89, v89
	v_add_f32_e32 v91, v91, v199
	v_exp_f32_e32 v91, v91
	v_mul_f32_e32 v88, 0xbf60028a, v88
	v_mul_f32_e32 v89, 0xbf60028a, v89
	v_exp_f32_e32 v88, v88
	v_exp_f32_e32 v89, v89
	v_add_f32_e32 v90, 1.0, v90
	v_rcp_f32_e32 v140, v90
	v_add_f32_e32 v90, 1.0, v91
	v_rcp_f32_e32 v141, v90


	v_mov_b32_e32 v198, 1.0


	v_mul_f32_dpp v88, v88, v88 row_shr:1 row_mask:0xf bank_mask:0xf
	v_mul_f32_dpp v89, v89, v89 row_shr:1 row_mask:0xf bank_mask:0xf


	v_mov_b32_e32 v199, 1.0


	v_mul_f32_dpp v88, v88, v88 row_shr:2 row_mask:0xf bank_mask:0xf
	v_mul_f32_dpp v89, v89, v89 row_shr:2 row_mask:0xf bank_mask:0xf


	v_mov_b32_e32 v233, 1.0


	v_mul_f32_dpp v88, v88, v88 row_shr:4 row_mask:0xf bank_mask:0xf
	v_mul_f32_dpp v89, v89, v89 row_shr:4 row_mask:0xf bank_mask:0xf


	s_nop 0


	v_mul_f32_dpp v88, v88, v88 row_shr:8 row_mask:0xf bank_mask:0xf
	v_mul_f32_dpp v89, v89, v89 row_shr:8 row_mask:0xf bank_mask:0xf
	v_mov_b64_e32 v[196:197], v[88:89]
	v_mul_f32_e32 v90, 0xbf60028a, v140
	v_mul_f32_e32 v91, 0xbf60028a, v141
	v_exp_f32_e32 v90, v90
	v_exp_f32_e32 v91, v91


	v_mov_b32_dpp v198, v196 row_shr:1 row_mask:0xf bank_mask:0xf


	v_mul_f32_dpp v90, v90, v90 row_shr:1 row_mask:0xf bank_mask:0xf
	v_mul_f32_dpp v91, v91, v91 row_shr:1 row_mask:0xf bank_mask:0xf


	s_nop 0
	v_mul_f32_dpp v90, v90, v90 row_shr:2 row_mask:0xf bank_mask:0xf
	v_mul_f32_dpp v91, v91, v91 row_shr:2 row_mask:0xf bank_mask:0xf


	v_mov_b32_dpp v199, v197 row_shr:1 row_mask:0xf bank_mask:0xf


	v_mul_f32_dpp v90, v90, v90 row_shr:4 row_mask:0xf bank_mask:0xf
	v_mul_f32_dpp v91, v91, v91 row_shr:4 row_mask:0xf bank_mask:0xf


	s_nop 0
	v_mul_f32_dpp v90, v90, v90 row_shr:8 row_mask:0xf bank_mask:0xf
	v_mul_f32_dpp v91, v91, v91 row_shr:8 row_mask:0xf bank_mask:0xf
	v_mov_b64_e32 v[230:231], v[90:91]
	s_nop 1
	v_mov_b32_dpp v232, v230 row_shr:1 row_mask:0xf bank_mask:0xf

	v_mov_b32_dpp v233, v231 row_shr:1 row_mask:0xf bank_mask:0xf

	s_and_saveexec_b64 s[34:35], s[40:41]
	ds_write_b64 v236, v[196:197] offset:26048
	ds_write_b64 v236, v[230:231] offset:26056
	s_or_b64 exec, exec, s[34:35]
	v_lshlrev_b32_e32 v140, 16, v138
	v_and_b32_e32 v141, 0xffff0000, v138
	v_lshlrev_b32_e32 v138, 16, v139
	v_and_b32_e32 v139, 0xffff0000, v139
	s_waitcnt lgkmcnt(2)
	v_add_f32_e32 v84, v84, v122
	v_mul_f32_e32 v88, v214, v138
	v_mul_f32_e32 v89, v215, v139
	v_exp_f32_e32 v84, v84
	v_add_f32_e32 v85, v85, v123
	v_mul_f32_e32 v90, v212, v140
	v_mul_f32_e32 v91, v213, v141
	v_fma_f32 v88, v88, v110, 0
	v_fma_f32 v89, v89, v111, 0
	v_lshlrev_b32_e32 v110, 16, v137
	v_and_b32_e32 v111, 0xffff0000, v137
	v_exp_f32_e32 v85, v85
	v_add_f32_e32 v86, v86, v124
	v_fma_f32 v90, v90, v108, 0
	v_fma_f32 v91, v91, v109, 0
	v_lshlrev_b32_e32 v108, 16, v136
	v_and_b32_e32 v109, 0xffff0000, v136
	v_mul_f32_e32 v200, v226, v110
	v_mul_f32_e32 v201, v227, v111
	v_exp_f32_e32 v86, v86
	v_add_f32_e32 v87, v87, v125
	v_mul_f32_e32 v136, v228, v108
	v_mul_f32_e32 v137, v229, v109
	v_fma_f32 v88, v200, v120, v88
	v_fma_f32 v89, v201, v121, v89
	v_lshlrev_b32_e32 v120, 16, v134
	v_and_b32_e32 v121, 0xffff0000, v134
	v_lshlrev_b32_e32 v134, 16, v135
	v_and_b32_e32 v135, 0xffff0000, v135
	v_exp_f32_e32 v87, v87
	v_fma_f32 v90, v136, v118, v90
	v_fma_f32 v91, v137, v119, v91
	v_mul_f32_e32 v118, v234, v134
	v_mul_f32_e32 v119, v235, v135
	v_mul_f32_e32 v114, v114, v120
	v_mul_f32_e32 v115, v115, v121
	v_add_f32_e32 v84, 1.0, v84
	v_fma_f32 v90, v114, v126, v90
	v_fma_f32 v91, v115, v127, v91
	v_fma_f32 v126, v118, v128, v88
	v_fma_f32 v127, v119, v129, v89
	v_rcp_f32_e32 v88, v84
	v_add_f32_e32 v84, 1.0, v85
	v_rcp_f32_e32 v89, v84
	v_add_f32_e32 v84, 1.0, v86
	v_rcp_f32_e32 v114, v84
	v_add_f32_e32 v84, 1.0, v87
	v_rcp_f32_e32 v115, v84
	v_rcp_f32_e32 v118, v196
	v_rcp_f32_e32 v119, v197
	v_rcp_f32_e32 v122, v230
	v_rcp_f32_e32 v123, v231
	s_waitcnt lgkmcnt(1)
	v_mul_f32_e32 v84, v98, v180
	v_mul_f32_e32 v85, v99, v181
	v_mul_f32_e32 v96, v96, v150
	v_mul_f32_e32 v97, v97, v151
	v_mov_b32_e32 v86, v194
	v_mov_b32_e32 v87, v194
	v_mul_f32_e32 v86, v86, v84
	v_mul_f32_e32 v87, v87, v85
	v_mul_f32_e32 v84, v194, v96
	v_mul_f32_e32 v85, v195, v97
	v_add_f32_e32 v96, -1.0, v88
	v_add_f32_e32 v97, -1.0, v89
	v_add_f32_e32 v98, -1.0, v114
	v_add_f32_e32 v99, -1.0, v115
	s_waitcnt lgkmcnt(0)
	v_fma_f32 v92, v92, v96, 1.0
	v_fma_f32 v93, v93, v97, 1.0
	v_fma_f32 v94, v94, v98, 1.0
	v_fma_f32 v95, v95, v99, 1.0
	v_mul_f32_e32 v98, v92, v150
	v_mul_f32_e32 v99, v93, v151
	v_mul_f32_e32 v124, v94, v180
	v_mul_f32_e32 v125, v95, v181
	v_mul_f32_e32 v92, v86, v114
	v_mul_f32_e32 v93, v87, v115
	v_mul_f32_e32 v88, v84, v88
	v_mul_f32_e32 v89, v85, v89
	v_mul_f32_e32 v94, v124, v122
	v_mul_f32_e32 v95, v125, v123
	v_mul_f32_e32 v96, v98, v118
	v_mul_f32_e32 v97, v99, v119
	v_mul_f32_e32 v92, v92, v122
	v_mul_f32_e32 v93, v93, v123
	v_mul_f32_e32 v88, v88, v118
	v_mul_f32_e32 v89, v89, v119
	v_cvt_pk_bf16_f32 v118, v96, v97
	v_cvt_pk_bf16_f32 v119, v94, v95
	v_cvt_pk_bf16_f32 v114, v88, v89
	v_cvt_pk_bf16_f32 v115, v92, v93
	ds_write_b64 v2, v[118:119] offset:21344
	ds_write_b64 v2, v[114:115] offset:23648
	ds_read_b128 v[94:97], v247 offset:18368
	v_lshlrev_b32_e32 v88, 16, v132
	v_and_b32_e32 v89, 0xffff0000, v132
	v_lshlrev_b32_e32 v92, 16, v133
	v_and_b32_e32 v93, 0xffff0000, v133
	v_mul_f32_e32 v98, v98, v88
	v_mul_f32_e32 v99, v99, v89
	v_mul_f32_e32 v122, v124, v92
	v_mul_f32_e32 v123, v125, v93
	s_waitcnt lgkmcnt(0)
	v_fma_f32 v90, v98, v94, v90
	v_fma_f32 v91, v99, v95, v91
	v_fma_f32 v96, v122, v96, v126
	v_fma_f32 v97, v123, v97, v127
	v_add_f32_e32 v90, v90, v91
	v_add_f32_e32 v91, v96, v97
	v_add_f32_e32 v90, v90, v91
	ds_bpermute_b32 v91, v248, v90
	s_add_i32 s70, s52, s55
	v_cmp_gt_u32_e32 vcc, 16, v239
	ds_write_b64 v2, v[0:1] offset:19040
	s_waitcnt lgkmcnt(1)
	v_add_f32_e32 v90, v90, v91
	ds_bpermute_b32 v91, v249, v90
	s_and_saveexec_b64 s[34:35], vcc
	s_cbranch_execz .LBB0_537
	v_sub_u32_e32 v1, s54, v237
	v_add3_u32 v0, s70, v237, -16
	v_add_u32_e32 v1, 3, v1
	v_cndmask_b32_e64 v0, v1, v0, s[38:39]
	v_add_u32_e32 v0, s53, v0
	s_waitcnt lgkmcnt(0)
	v_add_f32_e32 v1, v90, v91
	v_mul_f32_e32 v2, 0.5, v1
	v_ashrrev_i32_e32 v1, 31, v0
	v_lshl_add_u64 v[0:1], v[0:1], 0, s[8:9]
	v_lshlrev_b64 v[0:1], 6, v[0:1]
	v_lshl_add_u64 v[0:1], s[10:11], 0, v[0:1]
	global_store_dword v[0:1], v2, off
	s_branch .LBB0_537
